# HGRN raw proj reads non-temporal (HGRN streams have slack; keeps L2 for the critical mixers)
# speedup vs baseline: 1.0605x; 1.0029x over previous
.LBB0_759:
	v_readlane_b32 s4, v253, 21
	v_readlane_b32 s5, v253, 22
	v_readlane_b32 s8, v253, 23
	s_and_b32 s0, s1, 1
	s_ashr_i32 s2, s1, 3
	s_lshl_b64 s[4:5], s[4:5], 2
	v_readlane_b32 s12, v253, 27
	v_readlane_b32 s13, v253, 28
	s_add_u32 s4, s12, s4
	s_addc_u32 s5, s13, s5
	v_and_b32_e32 v1, 48, v4
	global_load_dwordx4 v[20:23], v1, s[4:5]
	global_load_dwordx4 v[24:27], v1, s[4:5] offset:64
	global_load_dwordx4 v[28:31], v1, s[4:5] offset:128
	global_load_dwordx4 v[32:35], v1, s[4:5] offset:192
	s_lshl_b32 s45, s0, 10
	s_lshr_b32 s1, s56, 6
	s_cmpk_lt_u32 s56, 0x100
	s_mul_hi_i32 s43, s2, 0x1100000
	s_cselect_b64 s[24:25], -1, 0
	s_cmpk_gt_u32 s56, 0xff
	s_mul_i32 s44, s2, 0x1100000
	s_mov_b64 s[52:53], 0x20000
	v_readlane_b32 s9, v253, 24
	v_readlane_b32 s10, v253, 25
	v_readlane_b32 s11, v253, 26
	v_readlane_b32 s14, v253, 29
	v_readlane_b32 s15, v253, 30
	v_readlane_b32 s16, v253, 31
	v_readlane_b32 s17, v253, 32
	v_readlane_b32 s18, v253, 33
	v_readlane_b32 s19, v253, 34
	v_readlane_b32 s20, v253, 35
	v_readlane_b32 s21, v253, 36
	v_readlane_b32 s22, v253, 37
	v_readlane_b32 s23, v253, 38
	s_cbranch_scc1 .LBB0_761
	v_readlane_b32 s4, v253, 45
	v_readlane_b32 s5, v253, 46
	s_add_u32 s3, s4, s44
	s_addc_u32 s6, s5, s43
	s_lshl_b32 s4, s1, 4
	s_or_b32 s4, s4, s45
	s_mul_i32 s92, s4, 0x1100
	s_lshl_b64 s[4:5], s[92:93], 1
	s_add_u32 s4, s3, s4
	s_addc_u32 s5, s6, s5
	v_lshlrev_b32_e32 v2, 1, v0
	v_lshl_add_u64 v[0:1], s[4:5], 0, v[2:3]
	v_add_co_u32_e32 v6, vcc, s63, v0
	global_load_ushort v8, v2, s[4:5] nt
	global_load_ushort v75, v2, s[4:5] offset:512 nt
	global_load_ushort v130, v2, s[4:5] offset:1024 nt
	v_addc_co_u32_e32 v7, vcc, 0, v1, vcc
	global_load_ushort v2, v[6:7], off offset:512 nt
	global_load_ushort v124, v[6:7], off offset:1024 nt
	global_load_ushort v129, v[6:7], off offset:1536 nt
	v_add_co_u32_e32 v6, vcc, s65, v0
	s_mov_b32 s3, 0xd000
	s_nop 0
	v_addc_co_u32_e32 v7, vcc, 0, v1, vcc
	global_load_ushort v9, v[6:7], off offset:1024 nt
	global_load_ushort v125, v[6:7], off offset:1536 nt
	global_load_ushort v131, v[6:7], off offset:2048 nt
	v_add_co_u32_e32 v6, vcc, s57, v0
	s_waitcnt vmcnt(5)
	v_perm_b32 v195, v8, v2, s71
	v_addc_co_u32_e32 v7, vcc, 0, v1, vcc
	global_load_ushort v10, v[6:7], off offset:1536 nt
	global_load_ushort v126, v[6:7], off offset:2048 nt
	global_load_ushort v133, v[6:7], off offset:2560 nt
	v_add_co_u32_e32 v6, vcc, s58, v0
	s_waitcnt vmcnt(2)
	v_perm_b32 v194, v9, v10, s71
	v_addc_co_u32_e32 v7, vcc, 0, v1, vcc
	global_load_ushort v11, v[6:7], off offset:2048 nt
	global_load_ushort v127, v[6:7], off offset:2560 nt
	global_load_ushort v134, v[6:7], off offset:3072 nt
	v_add_co_u32_e32 v6, vcc, s59, v0
	s_nop 1
	v_addc_co_u32_e32 v7, vcc, 0, v1, vcc
	global_load_ushort v12, v[6:7], off offset:2560 nt
	global_load_ushort v128, v[6:7], off offset:3072 nt
	global_load_ushort v132, v[6:7], off offset:3584 nt
	v_add_co_u32_e32 v6, vcc, s60, v0
	s_waitcnt vmcnt(2)
	v_perm_b32 v191, v11, v12, s71
	v_addc_co_u32_e32 v7, vcc, 0, v1, vcc
	global_load_ushort v13, v[6:7], off offset:3072 nt
	global_load_ushort v135, v[6:7], off offset:3584 nt
	v_add_co_u32_e32 v6, vcc, s3, v0
	s_mov_b32 s3, 0xf000
	s_nop 0
	v_addc_co_u32_e32 v7, vcc, 0, v1, vcc
	global_load_ushort v137, v[6:7], off nt
	v_add_co_u32_e32 v6, vcc, s61, v0
	s_nop 1
	v_addc_co_u32_e32 v7, vcc, 0, v1, vcc
	global_load_ushort v14, v[6:7], off offset:3584 nt
	v_add_co_u32_e32 v6, vcc, s3, v0
	s_mov_b32 s3, 0x11000
	s_nop 0
	v_addc_co_u32_e32 v7, vcc, 0, v1, vcc
	global_load_ushort v144, v[6:7], off nt
	global_load_ushort v136, v[6:7], off offset:512 nt
	v_add_co_u32_e32 v6, vcc, s3, v0
	s_mov_b32 s3, 0x13000
	s_nop 0
	v_addc_co_u32_e32 v7, vcc, 0, v1, vcc
	global_load_ushort v15, v[6:7], off nt
	global_load_ushort v146, v[6:7], off offset:512 nt
	global_load_ushort v140, v[6:7], off offset:1024 nt
	v_add_co_u32_e32 v6, vcc, s3, v0
	s_mov_b32 s3, 0x15000
	s_nop 0
	v_addc_co_u32_e32 v7, vcc, 0, v1, vcc
	global_load_ushort v16, v[6:7], off offset:512 nt
	global_load_ushort v148, v[6:7], off offset:1024 nt
	global_load_ushort v138, v[6:7], off offset:1536 nt
	v_add_co_u32_e32 v6, vcc, s3, v0
	s_mov_b32 s3, 0x17000
	s_nop 0
	v_addc_co_u32_e32 v7, vcc, 0, v1, vcc
	global_load_ushort v17, v[6:7], off offset:1024 nt
	global_load_ushort v150, v[6:7], off offset:1536 nt
	global_load_ushort v139, v[6:7], off offset:2048 nt
	v_add_co_u32_e32 v6, vcc, s3, v0
	s_mov_b32 s3, 0x19000
	s_nop 0
	v_addc_co_u32_e32 v7, vcc, 0, v1, vcc
	global_load_ushort v18, v[6:7], off offset:1536 nt
	global_load_ushort v152, v[6:7], off offset:2048 nt
	global_load_ushort v141, v[6:7], off offset:2560 nt
	v_add_co_u32_e32 v6, vcc, s3, v0
	s_mov_b32 s3, 0x1b000
	s_nop 0
	v_addc_co_u32_e32 v7, vcc, 0, v1, vcc
	global_load_ushort v19, v[6:7], off offset:2048 nt
	global_load_ushort v155, v[6:7], off offset:2560 nt
	global_load_ushort v143, v[6:7], off offset:3072 nt
	v_add_co_u32_e32 v6, vcc, s3, v0
	s_mov_b32 s3, 0x1d000
	s_nop 0
	v_addc_co_u32_e32 v7, vcc, 0, v1, vcc
	global_load_ushort v36, v[6:7], off offset:2560 nt
	global_load_ushort v183, v[6:7], off offset:3072 nt
	global_load_ushort v142, v[6:7], off offset:3584 nt
	v_add_co_u32_e32 v6, vcc, s3, v0
	s_mov_b32 s3, 0x1e000
	s_nop 0
	v_addc_co_u32_e32 v7, vcc, 0, v1, vcc
	global_load_ushort v37, v[6:7], off offset:3072 nt
	global_load_ushort v193, v[6:7], off offset:3584 nt
	v_add_co_u32_e32 v6, vcc, s3, v0
	s_mov_b32 s3, 0x1f000
	s_nop 0
	v_addc_co_u32_e32 v7, vcc, 0, v1, vcc
	global_load_ushort v145, v[6:7], off nt
	v_add_co_u32_e32 v6, vcc, s3, v0
	s_waitcnt vmcnt(23)
	v_perm_b32 v185, v13, v14, s71
	v_addc_co_u32_e32 v7, vcc, 0, v1, vcc
	v_add_co_u32_e32 v0, vcc, 0x20000, v0
	global_load_ushort v6, v[6:7], off offset:3584 nt
	s_nop 0
	v_addc_co_u32_e32 v1, vcc, 0, v1, vcc
	global_load_ushort v199, v[0:1], off nt
	global_load_ushort v147, v[0:1], off offset:512 nt
	s_waitcnt vmcnt(20)
	v_perm_b32 v173, v15, v16, s71
	s_waitcnt vmcnt(14)
	v_perm_b32 v168, v17, v18, s71
	s_waitcnt vmcnt(8)
	v_perm_b32 v153, v19, v36, s71
	s_waitcnt vmcnt(2)
	v_perm_b32 v151, v37, v6, s71

.Lhg_noz:
	v_mov_b32_e32 v223, v147
	v_cndmask_b32_e64 v2, v2, v4, s[18:19]
	v_cndmask_b32_e32 v4, 0, v233, vcc
	v_sub_f32_e32 v2, v2, v4
	v_add_f32_e32 v204, v2, v203
	v_lshlrev_b32_e32 v2, 16, v125
	v_mul_f32_e32 v2, 0xbfb8aa3b, v2
	v_exp_f32_e32 v2, v2
	s_nop 0
	v_add_f32_e32 v2, 1.0, v2
	v_rcp_f32_e32 v5, v2
	v_lshlrev_b32_e32 v2, 16, v126
	v_mul_f32_e32 v2, 0xbfb8aa3b, v2
	v_exp_f32_e32 v2, v2
	s_nop 0
	v_add_f32_e32 v2, 1.0, v2
	v_rcp_f32_e32 v4, v2
	s_nop 0
	v_pk_fma_f32 v[8:9], v[76:77], v[4:5], v[72:73]
	s_nop 0
	v_cmp_gt_f32_e32 vcc, s75, v9
	s_nop 1
	v_cndmask_b32_e64 v2, 0, 32, vcc
	v_ldexp_f32 v2, v9, v2
	v_log_f32_e32 v2, v2
	s_nop 0
	v_mul_f32_e32 v4, 0x3f317217, v2
	v_fma_f32 v4, v2, s88, -v4
	v_fmac_f32_e32 v4, 0x3377d1cf, v2
	v_fmac_f32_e32 v4, 0x3f317217, v2
	v_cmp_lt_f32_e64 s[18:19], |v2|, s70
	s_nop 1
	v_cndmask_b32_e64 v2, v2, v4, s[18:19]
	v_cndmask_b32_e32 v4, 0, v233, vcc
	v_sub_f32_e32 v2, v2, v4
	v_cmp_gt_f32_e32 vcc, s75, v8
	v_add_f32_e32 v205, v2, v204
	s_nop 0
	v_cndmask_b32_e64 v2, 0, 32, vcc
	v_ldexp_f32 v2, v8, v2
	v_log_f32_e32 v2, v2
	s_nop 0
	v_mul_f32_e32 v4, 0x3f317217, v2
	v_fma_f32 v4, v2, s88, -v4
	v_fmac_f32_e32 v4, 0x3377d1cf, v2
	v_fmac_f32_e32 v4, 0x3f317217, v2
	v_cmp_lt_f32_e64 s[18:19], |v2|, s70
	s_nop 1
	v_cndmask_b32_e64 v2, v2, v4, s[18:19]
	v_cndmask_b32_e32 v4, 0, v233, vcc
	v_sub_f32_e32 v2, v2, v4
	v_add_f32_e32 v206, v2, v205
	v_lshlrev_b32_e32 v2, 16, v127
	v_mul_f32_e32 v2, 0xbfb8aa3b, v2
	v_exp_f32_e32 v2, v2
	s_nop 0
	v_add_f32_e32 v2, 1.0, v2
	v_rcp_f32_e32 v5, v2
	v_lshlrev_b32_e32 v2, 16, v128
	v_mul_f32_e32 v2, 0xbfb8aa3b, v2
	v_exp_f32_e32 v2, v2
	s_nop 0
	v_add_f32_e32 v2, 1.0, v2
	v_rcp_f32_e32 v4, v2
	s_nop 0
	v_pk_fma_f32 v[10:11], v[76:77], v[4:5], v[72:73]
	s_nop 0
	v_cmp_gt_f32_e32 vcc, s75, v11
	s_nop 1
	v_cndmask_b32_e64 v2, 0, 32, vcc
	v_ldexp_f32 v2, v11, v2
	v_log_f32_e32 v2, v2
	s_nop 0
	v_mul_f32_e32 v4, 0x3f317217, v2
	v_fma_f32 v4, v2, s88, -v4
	v_fmac_f32_e32 v4, 0x3377d1cf, v2
	v_fmac_f32_e32 v4, 0x3f317217, v2
	v_cmp_lt_f32_e64 s[18:19], |v2|, s70
	s_nop 1
	v_cndmask_b32_e64 v2, v2, v4, s[18:19]
	v_cndmask_b32_e32 v4, 0, v233, vcc
	v_sub_f32_e32 v2, v2, v4
	v_cmp_gt_f32_e32 vcc, s75, v10
	v_add_f32_e32 v207, v2, v206
	s_nop 0
	v_cndmask_b32_e64 v2, 0, 32, vcc
	v_ldexp_f32 v2, v10, v2
	v_log_f32_e32 v2, v2
	s_nop 0
	v_mul_f32_e32 v4, 0x3f317217, v2
	v_fma_f32 v4, v2, s88, -v4
	v_fmac_f32_e32 v4, 0x3377d1cf, v2
	v_fmac_f32_e32 v4, 0x3f317217, v2
	v_cmp_lt_f32_e64 s[18:19], |v2|, s70
	s_nop 1
	v_cndmask_b32_e64 v2, v2, v4, s[18:19]
	v_cndmask_b32_e32 v4, 0, v233, vcc
	v_sub_f32_e32 v2, v2, v4
	v_add_f32_e32 v208, v2, v207
	v_lshlrev_b32_e32 v2, 16, v135
	v_mul_f32_e32 v2, 0xbfb8aa3b, v2
	v_exp_f32_e32 v2, v2
	s_nop 0
	v_add_f32_e32 v2, 1.0, v2
	v_rcp_f32_e32 v5, v2
	v_lshlrev_b32_e32 v2, 16, v144
	v_mul_f32_e32 v2, 0xbfb8aa3b, v2
	v_exp_f32_e32 v2, v2
	s_nop 0
	v_add_f32_e32 v2, 1.0, v2
	v_rcp_f32_e32 v4, v2
	s_nop 0
	v_pk_fma_f32 v[12:13], v[76:77], v[4:5], v[72:73]
	s_nop 0
	v_cmp_gt_f32_e32 vcc, s75, v13
	s_nop 1
	v_cndmask_b32_e64 v2, 0, 32, vcc
	v_ldexp_f32 v2, v13, v2
	v_log_f32_e32 v2, v2
	s_nop 0
	v_mul_f32_e32 v4, 0x3f317217, v2
	v_fma_f32 v4, v2, s88, -v4
	v_fmac_f32_e32 v4, 0x3377d1cf, v2
	v_fmac_f32_e32 v4, 0x3f317217, v2
	v_cmp_lt_f32_e64 s[18:19], |v2|, s70
	s_nop 1
	v_cndmask_b32_e64 v2, v2, v4, s[18:19]
	v_cndmask_b32_e32 v4, 0, v233, vcc
	v_sub_f32_e32 v2, v2, v4
	v_cmp_gt_f32_e32 vcc, s75, v12
	v_add_f32_e32 v209, v2, v208
	s_nop 0
	v_cndmask_b32_e64 v2, 0, 32, vcc
	v_ldexp_f32 v2, v12, v2
	v_log_f32_e32 v2, v2
	s_nop 0
	v_mul_f32_e32 v4, 0x3f317217, v2
	v_fma_f32 v4, v2, s88, -v4
	v_fmac_f32_e32 v4, 0x3377d1cf, v2
	v_fmac_f32_e32 v4, 0x3f317217, v2
	v_cmp_lt_f32_e64 s[18:19], |v2|, s70
	s_nop 1
	v_cndmask_b32_e64 v2, v2, v4, s[18:19]
	v_cndmask_b32_e32 v4, 0, v233, vcc
	v_sub_f32_e32 v2, v2, v4
	v_add_f32_e32 v210, v2, v209
	v_lshlrev_b32_e32 v2, 16, v146
	v_mul_f32_e32 v2, 0xbfb8aa3b, v2
	v_exp_f32_e32 v2, v2
	s_nop 0
	v_add_f32_e32 v2, 1.0, v2
	v_rcp_f32_e32 v5, v2
	v_lshlrev_b32_e32 v2, 16, v148
	v_mul_f32_e32 v2, 0xbfb8aa3b, v2
	v_exp_f32_e32 v2, v2
	s_nop 0
	v_add_f32_e32 v2, 1.0, v2
	v_rcp_f32_e32 v4, v2
	s_nop 0
	v_pk_fma_f32 v[14:15], v[76:77], v[4:5], v[72:73]
	s_nop 0
	v_cmp_gt_f32_e32 vcc, s75, v15
	s_nop 1
	v_cndmask_b32_e64 v2, 0, 32, vcc
	v_ldexp_f32 v2, v15, v2
	v_log_f32_e32 v2, v2
	s_nop 0
	v_mul_f32_e32 v4, 0x3f317217, v2
	v_fma_f32 v4, v2, s88, -v4
	v_fmac_f32_e32 v4, 0x3377d1cf, v2
	v_fmac_f32_e32 v4, 0x3f317217, v2
	v_cmp_lt_f32_e64 s[18:19], |v2|, s70
	s_nop 1
	v_cndmask_b32_e64 v2, v2, v4, s[18:19]
	v_cndmask_b32_e32 v4, 0, v233, vcc
	v_sub_f32_e32 v2, v2, v4
	v_cmp_gt_f32_e32 vcc, s75, v14
	v_add_f32_e32 v211, v2, v210
	s_nop 0
	v_cndmask_b32_e64 v2, 0, 32, vcc
	v_ldexp_f32 v2, v14, v2
	v_log_f32_e32 v2, v2
	s_nop 0
	v_mul_f32_e32 v4, 0x3f317217, v2
	v_fma_f32 v4, v2, s88, -v4
	v_fmac_f32_e32 v4, 0x3377d1cf, v2
	v_fmac_f32_e32 v4, 0x3f317217, v2
	v_cmp_lt_f32_e64 s[18:19], |v2|, s70
	s_nop 1
	v_cndmask_b32_e64 v2, v2, v4, s[18:19]
	v_cndmask_b32_e32 v4, 0, v233, vcc
	v_sub_f32_e32 v2, v2, v4
	v_add_f32_e32 v212, v2, v211
	v_lshlrev_b32_e32 v2, 16, v150
	v_mul_f32_e32 v2, 0xbfb8aa3b, v2
	v_exp_f32_e32 v2, v2
	s_nop 0
	v_add_f32_e32 v2, 1.0, v2
	v_rcp_f32_e32 v5, v2
	v_lshlrev_b32_e32 v2, 16, v152
	v_mul_f32_e32 v2, 0xbfb8aa3b, v2
	v_exp_f32_e32 v2, v2
	s_nop 0
	v_add_f32_e32 v2, 1.0, v2
	v_rcp_f32_e32 v4, v2
	s_nop 0
	v_pk_fma_f32 v[16:17], v[76:77], v[4:5], v[72:73]
	s_nop 0
	v_cmp_gt_f32_e32 vcc, s75, v17
	s_nop 1
	v_cndmask_b32_e64 v2, 0, 32, vcc
	v_ldexp_f32 v2, v17, v2
	v_log_f32_e32 v2, v2
	s_nop 0
	v_mul_f32_e32 v4, 0x3f317217, v2
	v_fma_f32 v4, v2, s88, -v4
	v_fmac_f32_e32 v4, 0x3377d1cf, v2
	v_fmac_f32_e32 v4, 0x3f317217, v2
	v_cmp_lt_f32_e64 s[18:19], |v2|, s70
	s_nop 1
	v_cndmask_b32_e64 v2, v2, v4, s[18:19]
	v_cndmask_b32_e32 v4, 0, v233, vcc
	v_sub_f32_e32 v2, v2, v4
	v_cmp_gt_f32_e32 vcc, s75, v16
	v_add_f32_e32 v213, v2, v212
	s_nop 0
	v_cndmask_b32_e64 v2, 0, 32, vcc
	v_ldexp_f32 v2, v16, v2
	v_log_f32_e32 v2, v2
	s_nop 0
	v_mul_f32_e32 v4, 0x3f317217, v2
	v_fma_f32 v4, v2, s88, -v4
	v_fmac_f32_e32 v4, 0x3377d1cf, v2
	v_fmac_f32_e32 v4, 0x3f317217, v2
	v_cmp_lt_f32_e64 s[18:19], |v2|, s70
	s_nop 1
	v_cndmask_b32_e64 v2, v2, v4, s[18:19]
	v_cndmask_b32_e32 v4, 0, v233, vcc
	v_sub_f32_e32 v2, v2, v4
	v_add_f32_e32 v214, v2, v213
	v_lshlrev_b32_e32 v2, 16, v155
	v_mul_f32_e32 v2, 0xbfb8aa3b, v2
	v_exp_f32_e32 v2, v2
	s_nop 0
	v_add_f32_e32 v2, 1.0, v2
	v_rcp_f32_e32 v5, v2
	v_lshlrev_b32_e32 v2, 16, v183
	v_mul_f32_e32 v2, 0xbfb8aa3b, v2
	v_exp_f32_e32 v2, v2
	s_nop 0
	v_add_f32_e32 v2, 1.0, v2
	v_rcp_f32_e32 v4, v2
	s_nop 0
	v_pk_fma_f32 v[18:19], v[76:77], v[4:5], v[72:73]
	s_nop 0
	v_cmp_gt_f32_e32 vcc, s75, v19
	s_nop 1
	v_cndmask_b32_e64 v2, 0, 32, vcc
	v_ldexp_f32 v2, v19, v2
	v_log_f32_e32 v2, v2
	s_nop 0
	v_mul_f32_e32 v4, 0x3f317217, v2
	v_fma_f32 v4, v2, s88, -v4
	v_fmac_f32_e32 v4, 0x3377d1cf, v2
	v_fmac_f32_e32 v4, 0x3f317217, v2
	v_cmp_lt_f32_e64 s[18:19], |v2|, s70
	s_nop 1
	v_cndmask_b32_e64 v2, v2, v4, s[18:19]
	v_cndmask_b32_e32 v4, 0, v233, vcc
	v_sub_f32_e32 v2, v2, v4
	v_cmp_gt_f32_e32 vcc, s75, v18
	v_add_f32_e32 v215, v2, v214
	s_nop 0
	v_cndmask_b32_e64 v2, 0, 32, vcc
	v_ldexp_f32 v2, v18, v2
	v_log_f32_e32 v2, v2
	s_nop 0
	v_mul_f32_e32 v4, 0x3f317217, v2
	v_fma_f32 v4, v2, s88, -v4
	v_fmac_f32_e32 v4, 0x3377d1cf, v2
	v_fmac_f32_e32 v4, 0x3f317217, v2
	v_cmp_lt_f32_e64 s[18:19], |v2|, s70
	s_nop 1
	v_cndmask_b32_e64 v2, v2, v4, s[18:19]
	v_cndmask_b32_e32 v4, 0, v233, vcc
	v_sub_f32_e32 v2, v2, v4
	v_add_f32_e32 v216, v2, v215
	v_lshlrev_b32_e32 v2, 16, v193
	v_mul_f32_e32 v2, 0xbfb8aa3b, v2
	v_exp_f32_e32 v2, v2
	s_nop 0
	v_add_f32_e32 v2, 1.0, v2
	v_rcp_f32_e32 v5, v2
	v_lshlrev_b32_e32 v2, 16, v199
	v_mul_f32_e32 v2, 0xbfb8aa3b, v2
	v_exp_f32_e32 v2, v2
	s_nop 0
	v_add_f32_e32 v2, 1.0, v2
	v_rcp_f32_e32 v4, v2
	s_nop 0
	v_pk_fma_f32 v[52:53], v[76:77], v[4:5], v[72:73]
	s_nop 0
	v_cmp_gt_f32_e32 vcc, s75, v53
	s_nop 1
	v_cndmask_b32_e64 v2, 0, 32, vcc
	v_ldexp_f32 v2, v53, v2
	v_log_f32_e32 v2, v2
	s_nop 0
	v_mul_f32_e32 v4, 0x3f317217, v2
	v_fma_f32 v4, v2, s88, -v4
	v_fmac_f32_e32 v4, 0x3377d1cf, v2
	v_fmac_f32_e32 v4, 0x3f317217, v2
	v_cmp_lt_f32_e64 s[18:19], |v2|, s70
	s_nop 1
	v_cndmask_b32_e64 v2, v2, v4, s[18:19]
	v_cndmask_b32_e32 v4, 0, v233, vcc
	v_sub_f32_e32 v2, v2, v4
	v_cmp_gt_f32_e32 vcc, s75, v52
	v_add_f32_e32 v217, v2, v216
	s_nop 0
	v_cndmask_b32_e64 v2, 0, 32, vcc
	v_ldexp_f32 v2, v52, v2
	v_log_f32_e32 v2, v2
	s_nop 0
	v_mul_f32_e32 v4, 0x3f317217, v2
	v_fma_f32 v4, v2, s88, -v4
	v_fmac_f32_e32 v4, 0x3377d1cf, v2
	v_fmac_f32_e32 v4, 0x3f317217, v2
	v_cmp_lt_f32_e64 s[18:19], |v2|, s70
	s_nop 1
	v_cndmask_b32_e64 v2, v2, v4, s[18:19]
	v_cndmask_b32_e32 v4, 0, v233, vcc
	v_sub_f32_e32 v2, v2, v4
	s_add_i32 s18, s40, 1
	v_add_f32_e32 v218, v2, v217
	s_cmp_ge_u32 s18, s41
	v_mov_b32_e32 v2, v130
	ds_write_b32 v161, v218 offset:64512
	s_cbranch_scc1 .LBB0_768
	v_lshl_add_u64 v[4:5], s[72:73], 0, v[78:79]
	v_add_co_u32_e32 v6, vcc, 0x3688000, v4
	s_nop 1
	v_addc_co_u32_e32 v7, vcc, 0, v5, vcc
	global_load_ushort v66, v[6:7], off nt
	global_load_ushort v75, v[6:7], off offset:512 nt
	global_load_ushort v2, v[6:7], off offset:1024 nt
	v_add_co_u32_e32 v6, vcc, 0x368a000, v4
	s_nop 1
	v_addc_co_u32_e32 v7, vcc, 0, v5, vcc
	global_load_ushort v94, v[6:7], off offset:512 nt
	global_load_ushort v124, v[6:7], off offset:1024 nt
	global_load_ushort v54, v[6:7], off offset:1536 nt
	v_add_co_u32_e32 v6, vcc, 0x368c000, v4
	s_nop 1
	v_addc_co_u32_e32 v7, vcc, 0, v5, vcc
	global_load_ushort v67, v[6:7], off offset:1024 nt
	global_load_ushort v125, v[6:7], off offset:1536 nt
	global_load_ushort v55, v[6:7], off offset:2048 nt
	v_add_co_u32_e32 v6, vcc, 0x368e000, v4
	s_nop 1
	v_addc_co_u32_e32 v7, vcc, 0, v5, vcc
	global_load_ushort v95, v[6:7], off offset:1536 nt
	global_load_ushort v126, v[6:7], off offset:2048 nt
	global_load_ushort v56, v[6:7], off offset:2560 nt
	v_add_co_u32_e32 v6, vcc, 0x3690000, v4
	s_nop 1
	v_addc_co_u32_e32 v7, vcc, 0, v5, vcc
	global_load_ushort v68, v[6:7], off offset:2048 nt
	global_load_ushort v127, v[6:7], off offset:2560 nt
	global_load_ushort v57, v[6:7], off offset:3072 nt
	v_add_co_u32_e32 v6, vcc, 0x3692000, v4
	s_nop 1
	v_addc_co_u32_e32 v7, vcc, 0, v5, vcc
	global_load_ushort v96, v[6:7], off offset:2560 nt
	global_load_ushort v128, v[6:7], off offset:3072 nt
	global_load_ushort v58, v[6:7], off offset:3584 nt
	v_add_co_u32_e32 v6, vcc, 0x3694000, v4
	s_nop 1
	v_addc_co_u32_e32 v7, vcc, 0, v5, vcc
	global_load_ushort v70, v[6:7], off offset:3072 nt
	global_load_ushort v135, v[6:7], off offset:3584 nt
	v_add_co_u32_e32 v6, vcc, 0x3695000, v4
	s_nop 1
	v_addc_co_u32_e32 v7, vcc, 0, v5, vcc
	global_load_ushort v59, v[6:7], off nt
	v_add_co_u32_e32 v6, vcc, 0x3696000, v4
	s_nop 1
	v_addc_co_u32_e32 v7, vcc, 0, v5, vcc
	global_load_ushort v97, v[6:7], off offset:3584 nt
	v_add_co_u32_e32 v6, vcc, 0x3697000, v4
	s_nop 1
	v_addc_co_u32_e32 v7, vcc, 0, v5, vcc
	global_load_ushort v144, v[6:7], off nt
	global_load_ushort v60, v[6:7], off offset:512 nt
	v_add_co_u32_e32 v6, vcc, 0x3699000, v4
	s_nop 1
	v_addc_co_u32_e32 v7, vcc, 0, v5, vcc
	global_load_ushort v71, v[6:7], off nt
	global_load_ushort v146, v[6:7], off offset:512 nt
	global_load_ushort v61, v[6:7], off offset:1024 nt
	v_add_co_u32_e32 v6, vcc, 0x369b000, v4
	s_nop 1
	v_addc_co_u32_e32 v7, vcc, 0, v5, vcc
	global_load_ushort v98, v[6:7], off offset:512 nt
	global_load_ushort v148, v[6:7], off offset:1024 nt
	global_load_ushort v62, v[6:7], off offset:1536 nt
	v_add_co_u32_e32 v6, vcc, 0x369d000, v4
	s_nop 1
	v_addc_co_u32_e32 v7, vcc, 0, v5, vcc
	global_load_ushort v99, v[6:7], off offset:1024 nt
	global_load_ushort v150, v[6:7], off offset:1536 nt
	global_load_ushort v63, v[6:7], off offset:2048 nt
	v_add_co_u32_e32 v6, vcc, 0x369f000, v4
	s_nop 1
	v_addc_co_u32_e32 v7, vcc, 0, v5, vcc
	global_load_ushort v100, v[6:7], off offset:1536 nt
	global_load_ushort v152, v[6:7], off offset:2048 nt
	global_load_ushort v64, v[6:7], off offset:2560 nt
	v_add_co_u32_e32 v6, vcc, 0x36a1000, v4
	s_nop 1
	v_addc_co_u32_e32 v7, vcc, 0, v5, vcc
	global_load_ushort v101, v[6:7], off offset:2048 nt
	global_load_ushort v155, v[6:7], off offset:2560 nt
	global_load_ushort v65, v[6:7], off offset:3072 nt
	v_add_co_u32_e32 v6, vcc, 0x36a3000, v4
	s_nop 1
	v_addc_co_u32_e32 v7, vcc, 0, v5, vcc
	global_load_ushort v102, v[6:7], off offset:2560 nt
	global_load_ushort v183, v[6:7], off offset:3072 nt
	global_load_ushort v69, v[6:7], off offset:3584 nt
	v_add_co_u32_e32 v6, vcc, 0x36a5000, v4
	s_nop 1
	v_addc_co_u32_e32 v7, vcc, 0, v5, vcc
	global_load_ushort v103, v[6:7], off offset:3072 nt
	global_load_ushort v193, v[6:7], off offset:3584 nt
	v_add_co_u32_e32 v6, vcc, 0x36a6000, v4
	s_nop 1
	v_addc_co_u32_e32 v7, vcc, 0, v5, vcc
	global_load_ushort v222, v[6:7], off nt
	v_add_co_u32_e32 v6, vcc, 0x36a7000, v4
	s_nop 1
	v_addc_co_u32_e32 v7, vcc, 0, v5, vcc
	v_add_co_u32_e32 v4, vcc, 0x36a8000, v4
	global_load_ushort v6, v[6:7], off offset:3584 nt
	s_nop 0
	v_addc_co_u32_e32 v5, vcc, 0, v5, vcc
	global_load_ushort v199, v[4:5], off nt
	global_load_ushort v223, v[4:5], off offset:512 nt
	s_waitcnt vmcnt(2)
	v_perm_b32 v66, v66, v94, s71
	v_perm_b32 v67, v67, v95, s71
	v_perm_b32 v68, v68, v96, s71
	v_perm_b32 v70, v70, v97, s71
	v_perm_b32 v71, v71, v98, s71
	v_perm_b32 v219, v99, v100, s71
	v_perm_b32 v220, v101, v102, s71
	v_perm_b32 v221, v103, v6, s71
